# swa output: four 8-byte stores per lane become two 16-byte stores after v_permlane16_swap pairs (64 contiguous bytes per query row per store)
# baseline (speedup 1.0000x reference)
; #define LAS __attribute__((address_space(3)))
; __device__ __forceinline__ unsigned pk2(float lo, float hi) { f32x2c v = {lo, hi}; return __builtin_bit_cast(unsigned, __builtin_convertvector(v, bf16x2c)); }
; __device__ __forceinline__ void swa_phase(const Params& p, LAS unsigned char* lds8, const int e) {
;     ...
;             mloc = fmaxf(mloc, __shfl_xor(mloc, 16)); mloc = fmaxf(mloc, __shfl_xor(mloc, 32));
;             const float mt = fmaxf(mloc, sink);
;             float l = 0.f;
; #pragma unroll
;             for (int t = 0; t < 10; ++t)
; #pragma unroll
;                 for (int r = 0; r < 4; ++r) { const float pp = __expf(S[t][r] - mt); S[t][r] = pp; l += pp; }
;             l += __shfl_xor(l, 16); l += __shfl_xor(l, 32);
;             const float inv = 1.f / (l + __expf(sink - mt));
;             f32x4 O[4];
; #pragma unroll
;             for (int dt = 0; dt < 4; ++dt) O[dt] = (f32x4){0.f, 0.f, 0.f, 0.f};
; #pragma unroll
;             for (int s = 0; s < 5; ++s) {
;                 u32x4 pw; pw.x = pk2(S[2 * s][0], S[2 * s][1]); pw.y = pk2(S[2 * s][2], S[2 * s][3]); pw.z = pk2(S[2 * s + 1][0], S[2 * s + 1][1]); pw.w = pk2(S[2 * s + 1][2], S[2 * s + 1][3]);
;                 const bf16x8 pb = __builtin_bit_cast(bf16x8, pw);
; #pragma unroll
;                 for (int dt = 0; dt < 4; ++dt) {
;                     const LAS unsigned short* vp = VTb + (16 * dt + fr) * SW_VS + 16 * (kt0 + 2 * s) + 4 * fq;
;                     const s16x4 v0 = *(const LAS s16x4*)vp; s16x4 v1 = (s16x4){0, 0, 0, 0}; if (s < 4) v1 = *(const LAS s16x4*)(vp + 16);
;                     const bf16x8 a = (bf16x8){v0[0], v0[1], v0[2], v0[3], v1[0], v1[1], v1[2], v1[3]};
;                     O[dt] = __builtin_amdgcn_mfma_f32_16x16x32_bf16(a, pb, O[dt], 0, 0, 0); }
.LBB0_1225:
	s_or_b64 exec, exec, s[12:13]
	v_max_f32_e32 v0, v2, v2
	v_max_f32_e32 v0, 0xf149f2ca, v0
	v_max3_f32 v0, v0, v1, v17
	v_max3_f32 v0, v0, v16, v19
	v_max3_f32 v0, v0, v18, v37
	v_max3_f32 v0, v0, v36, v39
	v_max3_f32 v0, v0, v38, v41
	v_max3_f32 v0, v0, v40, v43
	v_max3_f32 v0, v0, v42, v45
	v_max3_f32 v0, v0, v44, v47
	v_max3_f32 v0, v0, v46, v49
	v_max3_f32 v0, v0, v48, v51
	v_max3_f32 v0, v0, v50, v53
	v_max3_f32 v0, v0, v52, v55
	v_max3_f32 v0, v0, v54, v57
	v_max3_f32 v0, v0, v56, v59
	v_and_b32_e32 v7, 64, v152
	v_max3_f32 v0, v0, v58, v13
	v_xor_b32_e32 v6, 16, v152
	v_add_u32_e32 v7, 64, v7
	v_max3_f32 v0, v0, v12, v9
	v_cmp_lt_i32_e32 vcc, v6, v7
	v_max3_f32 v0, v0, v8, v5
	s_mov_b32 s12, 0xf149f2ca
	v_cndmask_b32_e32 v6, v152, v6, vcc
	v_max3_f32 v0, v0, v4, s12
	v_lshlrev_b32_e32 v6, 2, v6
	ds_bpermute_b32 v10, v6, v0
	s_or_b64 s[10:11], s[10:11], s[8:9]
	s_waitcnt lgkmcnt(0)
	v_max_f32_e32 v10, v10, v10
	v_max_f32_e32 v0, v0, v10
	v_xor_b32_e32 v10, 32, v152
	v_cmp_lt_i32_e32 vcc, v10, v7
	s_nop 1
	v_cndmask_b32_e32 v7, v152, v10, vcc
	v_lshlrev_b32_e32 v7, 2, v7
	ds_bpermute_b32 v10, v7, v0
	s_waitcnt vmcnt(0) lgkmcnt(0)
	v_max3_f32 v25, v0, v10, v23
	v_sub_f32_e32 v1, v1, v25
	v_mul_f32_e32 v1, 0x3fb8aa3b, v1
	v_exp_f32_e32 v11, v1
	v_sub_f32_e32 v1, v17, v25
	v_mul_f32_e32 v1, 0x3fb8aa3b, v1
	v_exp_f32_e32 v60, v1
	v_sub_f32_e32 v1, v16, v25
	v_mul_f32_e32 v1, 0x3fb8aa3b, v1
	v_exp_f32_e32 v61, v1
	v_sub_f32_e32 v1, v19, v25
	v_mul_f32_e32 v1, 0x3fb8aa3b, v1
	v_exp_f32_e32 v19, v1
	v_sub_f32_e32 v1, v18, v25
	v_mul_f32_e32 v1, 0x3fb8aa3b, v1
	v_exp_f32_e32 v18, v1
	v_sub_f32_e32 v1, v37, v25
	v_mul_f32_e32 v1, 0x3fb8aa3b, v1
	v_exp_f32_e32 v62, v1
	v_sub_f32_e32 v1, v36, v25
	v_mul_f32_e32 v1, 0x3fb8aa3b, v1
	v_exp_f32_e32 v63, v1
	v_sub_f32_e32 v1, v39, v25
	v_mul_f32_e32 v1, 0x3fb8aa3b, v1
	v_exp_f32_e32 v66, v1
	v_sub_f32_e32 v1, v38, v25
	v_mul_f32_e32 v1, 0x3fb8aa3b, v1
	v_exp_f32_e32 v67, v1
	v_sub_f32_e32 v1, v41, v25
	v_mul_f32_e32 v1, 0x3fb8aa3b, v1
	v_exp_f32_e32 v68, v1
	v_sub_f32_e32 v1, v40, v25
	v_mul_f32_e32 v1, 0x3fb8aa3b, v1
	v_exp_f32_e32 v69, v1
	v_sub_f32_e32 v1, v43, v25
	v_mul_f32_e32 v1, 0x3fb8aa3b, v1
	v_exp_f32_e32 v70, v1
	v_sub_f32_e32 v1, v42, v25
	v_mul_f32_e32 v1, 0x3fb8aa3b, v1
	v_exp_f32_e32 v71, v1
	v_sub_f32_e32 v1, v45, v25
	v_mul_f32_e32 v1, 0x3fb8aa3b, v1
	v_exp_f32_e32 v72, v1
	v_sub_f32_e32 v1, v44, v25
	v_sub_f32_e32 v0, v2, v25
	v_mul_f32_e32 v1, 0x3fb8aa3b, v1
	v_mul_f32_e32 v0, 0x3fb8aa3b, v0
	v_exp_f32_e32 v73, v1
	v_sub_f32_e32 v1, v47, v25
	v_exp_f32_e32 v10, v0
	v_mul_f32_e32 v1, 0x3fb8aa3b, v1
	v_exp_f32_e32 v74, v1
	v_sub_f32_e32 v1, v46, v25
	v_mul_f32_e32 v1, 0x3fb8aa3b, v1
	v_exp_f32_e32 v75, v1
	v_sub_f32_e32 v1, v49, v25
	v_add_f32_e32 v0, 0, v10
	v_mul_f32_e32 v1, 0x3fb8aa3b, v1
	v_add_f32_e32 v0, v11, v0
	v_exp_f32_e32 v76, v1
	v_sub_f32_e32 v1, v48, v25
	v_add_f32_e32 v0, v60, v0
	v_mul_f32_e32 v1, 0x3fb8aa3b, v1
	v_add_f32_e32 v0, v61, v0
	v_exp_f32_e32 v77, v1
	v_sub_f32_e32 v1, v51, v25
	v_add_f32_e32 v0, v19, v0
	v_mul_f32_e32 v1, 0x3fb8aa3b, v1
	v_add_f32_e32 v0, v18, v0
	v_exp_f32_e32 v78, v1
	v_sub_f32_e32 v1, v50, v25
	v_add_f32_e32 v0, v62, v0
	v_mul_f32_e32 v1, 0x3fb8aa3b, v1
	v_add_f32_e32 v0, v63, v0
	v_exp_f32_e32 v79, v1
	v_sub_f32_e32 v1, v53, v25
	v_add_f32_e32 v0, v66, v0
	v_mul_f32_e32 v1, 0x3fb8aa3b, v1
	v_add_f32_e32 v0, v67, v0
	v_exp_f32_e32 v80, v1
	v_sub_f32_e32 v1, v52, v25
	v_add_f32_e32 v0, v68, v0
	v_mul_f32_e32 v1, 0x3fb8aa3b, v1
	v_add_f32_e32 v0, v69, v0
	v_exp_f32_e32 v81, v1
	v_sub_f32_e32 v1, v55, v25
	v_add_f32_e32 v0, v70, v0
	v_mul_f32_e32 v1, 0x3fb8aa3b, v1
	v_add_f32_e32 v0, v71, v0
	v_exp_f32_e32 v14, v1
	v_sub_f32_e32 v1, v54, v25
	v_add_f32_e32 v0, v72, v0
	v_mul_f32_e32 v1, 0x3fb8aa3b, v1
	v_add_f32_e32 v0, v73, v0
	v_exp_f32_e32 v15, v1
	v_sub_f32_e32 v1, v57, v25
	v_add_f32_e32 v0, v74, v0
	v_mul_f32_e32 v1, 0x3fb8aa3b, v1
	v_add_f32_e32 v0, v75, v0
	v_exp_f32_e32 v16, v1
	v_sub_f32_e32 v1, v56, v25
	v_add_f32_e32 v0, v76, v0
	v_mul_f32_e32 v1, 0x3fb8aa3b, v1
	v_add_f32_e32 v0, v77, v0
	v_exp_f32_e32 v17, v1
	v_sub_f32_e32 v1, v59, v25
	v_add_f32_e32 v0, v78, v0
	v_mul_f32_e32 v1, 0x3fb8aa3b, v1
	v_add_f32_e32 v0, v79, v0
	v_exp_f32_e32 v82, v1
	v_sub_f32_e32 v1, v58, v25
	v_add_f32_e32 v0, v80, v0
	v_mul_f32_e32 v1, 0x3fb8aa3b, v1
	v_add_f32_e32 v0, v81, v0
	v_exp_f32_e32 v83, v1
	v_sub_f32_e32 v1, v13, v25
	v_add_f32_e32 v0, v14, v0
	v_mul_f32_e32 v1, 0x3fb8aa3b, v1
	v_add_f32_e32 v0, v15, v0
	v_exp_f32_e32 v84, v1
	v_sub_f32_e32 v1, v12, v25
	v_add_f32_e32 v0, v16, v0
	v_mul_f32_e32 v1, 0x3fb8aa3b, v1
	v_add_f32_e32 v0, v17, v0
	v_exp_f32_e32 v85, v1
	v_add_f32_e32 v0, v82, v0
	v_add_f32_e32 v0, v83, v0
	v_add_f32_e32 v0, v84, v0
	v_add_f32_e32 v1, v85, v0
	v_sub_f32_e32 v0, v9, v25
	v_mul_f32_e32 v0, 0x3fb8aa3b, v0
	v_exp_f32_e32 v0, v0
	v_sub_f32_e32 v4, v4, v25
	v_mul_f32_e32 v4, 0x3fb8aa3b, v4
	v_exp_f32_e32 v12, v4
	v_add_f32_e32 v2, v0, v1
	v_sub_f32_e32 v1, v8, v25
	v_mul_f32_e32 v1, 0x3fb8aa3b, v1
	v_exp_f32_e32 v1, v1
	v_cvt_pk_bf16_f32 v40, v19, v18
	v_lshl_add_u32 v18, s30, 5, v35
	v_add_u32_e32 v19, 0x5800, v18
	v_add_f32_e32 v8, v1, v2
	v_sub_f32_e32 v2, v5, v25
	v_mul_f32_e32 v2, 0x3fb8aa3b, v2
	v_exp_f32_e32 v2, v2
	v_add_u32_e32 v86, 0x6800, v18
	v_cvt_pk_bf16_f32 v38, v10, v11
	v_cvt_pk_bf16_f32 v39, v60, v61
	v_add_f32_e32 v5, v2, v8
	v_add_f32_e32 v4, v12, v5
	v_sub_f32_e32 v5, 0xf149f2ca, v25
	v_mul_f32_e32 v5, 0x3fb8aa3b, v5
	v_exp_f32_e32 v13, v5
	v_cvt_pk_bf16_f32 v41, v62, v63
	v_add_u32_e32 v10, 0x100, v18
	ds_read2_b64 v[46:49], v86 offset0:228 offset1:232
	v_add_f32_e32 v4, v13, v4
	v_add_f32_e32 v4, v13, v4
	v_add_f32_e32 v4, v13, v4
	v_add_f32_e32 v4, v13, v4
	ds_bpermute_b32 v5, v6, v4
	s_waitcnt lgkmcnt(1)
; #define LAS __attribute__((address_space(3)))
; __device__ __forceinline__ unsigned pk2(float lo, float hi) { f32x2c v = {lo, hi}; return __builtin_bit_cast(unsigned, __builtin_convertvector(v, bf16x2c)); }
; __device__ __forceinline__ void swa_phase(const Params& p, LAS unsigned char* lds8, const int e) {
;     ...
;             for (int s = 0; s < 5; ++s) {
;                 u32x4 pw; pw.x = pk2(S[2 * s][0], S[2 * s][1]); pw.y = pk2(S[2 * s][2], S[2 * s][3]); pw.z = pk2(S[2 * s + 1][0], S[2 * s + 1][1]); pw.w = pk2(S[2 * s + 1][2], S[2 * s + 1][3]);
;                 const bf16x8 pb = __builtin_bit_cast(bf16x8, pw);
; #pragma unroll
;                 for (int dt = 0; dt < 4; ++dt) {
;                     const LAS unsigned short* vp = VTb + (16 * dt + fr) * SW_VS + 16 * (kt0 + 2 * s) + 4 * fq;
;                     const s16x4 v0 = *(const LAS s16x4*)vp; s16x4 v1 = (s16x4){0, 0, 0, 0}; if (s < 4) v1 = *(const LAS s16x4*)(vp + 16);
;                     const bf16x8 a = (bf16x8){v0[0], v0[1], v0[2], v0[3], v1[0], v1[1], v1[2], v1[3]};
;                     O[dt] = __builtin_amdgcn_mfma_f32_16x16x32_bf16(a, pb, O[dt], 0, 0, 0); }
;             }
;             if (qreal) {
;                 bf16_t* dst = MA + (size_t)mtok * D + 1024 + head * 64 + 4 * fq;
; #pragma unroll
;                 for (int dt = 0; dt < 4; ++dt) { u32x2 w; w.x = pk2(O[dt][0] * inv, O[dt][1] * inv); w.y = pk2(O[dt][2] * inv, O[dt][3] * inv); *(u32x2*)(dst + 16 * dt) = w; }
;             }
	v_mov_b32_e32 v8, v46
	v_mov_b32_e32 v9, v47
	v_add_u32_e32 v87, 0x8000, v18
	v_mov_b32_e32 v46, v48
	s_waitcnt lgkmcnt(0)
	v_add_f32_e32 v36, v4, v5
	ds_bpermute_b32 v37, v7, v36
	ds_read2_b64 v[4:7], v19 offset0:64 offset1:68
	s_waitcnt lgkmcnt(0)
	v_mfma_f32_16x16x32_bf16 v[42:45], v[4:7], v[38:41], 0
	ds_read2st64_b64 v[4:7], v10 offset0:45 offset1:55
	v_mov_b32_e32 v47, v49
	v_cvt_pk_bf16_f32 v14, v14, v15
	s_waitcnt lgkmcnt(0)
	v_mfma_f32_16x16x32_bf16 v[50:53], v[6:9], v[38:41], 0
	ds_read2_b64 v[6:9], v87 offset0:128 offset1:132
	v_cvt_pk_bf16_f32 v15, v16, v17
	v_cvt_pk_bf16_f32 v16, v82, v83
	s_waitcnt lgkmcnt(0)
	v_mfma_f32_16x16x32_bf16 v[54:57], v[6:9], v[38:41], 0
	v_add_u32_e32 v6, 0x9800, v18
	ds_read2st64_b64 v[8:11], v10 offset0:66 offset1:76
	ds_read2_b64 v[58:61], v6 offset0:36 offset1:40
	v_cvt_pk_bf16_f32 v17, v84, v85
	v_add_u32_e32 v7, 0x6c00, v18
	s_waitcnt lgkmcnt(1)
	v_mov_b32_e32 v62, v10
	v_mov_b32_e32 v63, v11
	s_waitcnt lgkmcnt(0)
	v_mov_b32_e32 v64, v58
	v_mov_b32_e32 v65, v59
	v_mov_b32_e32 v58, v60
	v_mov_b32_e32 v59, v61
	v_mfma_f32_16x16x32_bf16 v[38:41], v[62:65], v[38:41], 0
	v_cvt_pk_bf16_f32 v62, v66, v67
	v_cvt_pk_bf16_f32 v63, v68, v69
	ds_read2_b64 v[66:69], v19 offset0:72 offset1:76
	v_cvt_pk_bf16_f32 v64, v70, v71
	v_cvt_pk_bf16_f32 v65, v72, v73
	v_mov_b32_e32 v10, v3
	v_mov_b32_e32 v11, v3
	s_waitcnt lgkmcnt(0)
	v_mfma_f32_16x16x32_bf16 v[42:45], v[66:69], v[62:65], v[42:45]
	ds_read2_b64 v[66:69], v86 offset0:236 offset1:240
	s_waitcnt lgkmcnt(0)
	v_mov_b32_e32 v48, v66
	v_mov_b32_e32 v49, v67
	v_mov_b32_e32 v66, v68
	v_mov_b32_e32 v67, v69
	v_mfma_f32_16x16x32_bf16 v[46:49], v[46:49], v[62:65], v[50:53]
	s_nop 2
	ds_read2_b64 v[50:53], v87 offset0:136 offset1:140
	s_waitcnt lgkmcnt(0)
	v_mfma_f32_16x16x32_bf16 v[50:53], v[50:53], v[62:65], v[54:57]
	s_nop 2
	ds_read2_b64 v[54:57], v6 offset0:44 offset1:48
	s_waitcnt lgkmcnt(0)
	v_mov_b32_e32 v60, v54
	v_mov_b32_e32 v61, v55
	v_mov_b32_e32 v54, v56
	v_mov_b32_e32 v55, v57
	v_mfma_f32_16x16x32_bf16 v[38:41], v[58:61], v[62:65], v[38:41]
	ds_read2_b64 v[62:65], v19 offset0:80 offset1:84
	v_cvt_pk_bf16_f32 v58, v74, v75
	v_cvt_pk_bf16_f32 v59, v76, v77
	v_cvt_pk_bf16_f32 v60, v78, v79
	v_cvt_pk_bf16_f32 v61, v80, v81
	s_waitcnt lgkmcnt(0)
	s_nop 0
	v_mfma_f32_16x16x32_bf16 v[42:45], v[62:65], v[58:61], v[42:45]
	ds_read2_b64 v[62:65], v86 offset0:244 offset1:248
	s_waitcnt lgkmcnt(0)
	v_mov_b32_e32 v68, v62
	v_mov_b32_e32 v69, v63
	s_nop 1
	v_mfma_f32_16x16x32_bf16 v[46:49], v[66:69], v[58:61], v[46:49]
	ds_read2_b64 v[66:69], v87 offset0:144 offset1:148
	s_waitcnt lgkmcnt(0)
	v_mfma_f32_16x16x32_bf16 v[50:53], v[66:69], v[58:61], v[50:53]
	ds_read2_b64 v[66:69], v6 offset0:52 offset1:56
	s_waitcnt lgkmcnt(0)
	v_mov_b32_e32 v56, v66
	v_mov_b32_e32 v57, v67
	v_mov_b32_e32 v62, v68
	v_mov_b32_e32 v63, v69
	v_mfma_f32_16x16x32_bf16 v[38:41], v[54:57], v[58:61], v[38:41]
	ds_read2_b64 v[54:57], v19 offset0:88 offset1:92
	v_mov_b32_e32 v58, v64
	v_mov_b32_e32 v59, v65
	s_waitcnt lgkmcnt(0)
	v_mfma_f32_16x16x32_bf16 v[42:45], v[54:57], v[14:17], v[42:45]
	ds_read2_b64 v[54:57], v7 offset0:124 offset1:128
	v_mov_b32_e32 v7, v3
	s_waitcnt lgkmcnt(0)
	v_mov_b32_e32 v60, v54
	v_mov_b32_e32 v61, v55
	s_nop 1
	v_mfma_f32_16x16x32_bf16 v[46:49], v[58:61], v[14:17], v[46:49]
	ds_read2_b64 v[58:61], v87 offset0:152 offset1:156
	s_waitcnt lgkmcnt(0)
	v_mfma_f32_16x16x32_bf16 v[50:53], v[58:61], v[14:17], v[50:53]
	ds_read2_b64 v[58:61], v6 offset0:60 offset1:64
	v_mov_b32_e32 v6, v3
	s_waitcnt lgkmcnt(0)
	v_mov_b32_e32 v64, v58
	v_mov_b32_e32 v65, v59
	s_nop 1
	v_mfma_f32_16x16x32_bf16 v[16:19], v[62:65], v[14:17], v[38:41]
	s_nop 2
	v_cvt_pk_bf16_f32 v38, v0, v1
	v_cvt_pk_bf16_f32 v39, v2, v12
	v_mov_b32_e32 v0, v56
	v_mov_b32_e32 v1, v57
	v_mov_b32_e32 v2, v3
	v_cvt_pk_bf16_f32 v40, v13, v13
	v_mov_b32_e32 v41, v40
	s_nop 1
	v_mfma_f32_16x16x32_bf16 v[12:15], v[4:7], v[38:41], v[42:45]
	v_mfma_f32_16x16x32_bf16 v[4:7], v[0:3], v[38:41], v[46:49]
	v_mov_b32_e32 v0, v60
	v_mov_b32_e32 v1, v61
	v_mfma_f32_16x16x32_bf16 v[8:11], v[8:11], v[38:41], v[50:53]
	s_nop 0
	v_mfma_f32_16x16x32_bf16 v[16:19], v[0:3], v[38:41], v[16:19]
	s_and_saveexec_b64 s[12:13], s[10:11]
	s_cbranch_execz .LBB0_1127
	v_sub_f32_e32 v0, v23, v25
	v_mul_f32_e32 v0, 0x3fb8aa3b, v0
	v_exp_f32_e32 v0, v0
	v_add_f32_e32 v1, v36, v37
	v_ashrrev_i32_e32 v25, 31, v24
	v_lshlrev_b64 v[24:25], 12, v[24:25]
	v_add_f32_e32 v0, v0, v1
	v_div_scale_f32 v1, s[10:11], v0, v0, 1.0
	v_rcp_f32_e32 v2, v1
	v_div_scale_f32 v23, vcc, 1.0, v0, 1.0
	v_lshl_add_u64 v[24:25], s[20:21], 0, v[24:25]
	v_fma_f32 v36, -v1, v2, 1.0
	v_fmac_f32_e32 v2, v36, v2
	v_mul_f32_e32 v36, v23, v2
	v_fma_f32 v37, -v1, v36, v23
	v_fmac_f32_e32 v36, v37, v2
	v_fma_f32 v1, -v1, v36, v23
	v_div_fmas_f32 v1, v1, v2, v36
	v_div_fixup_f32 v0, v1, v0, 1.0
	v_lshl_add_u64 v[24:25], s[24:25], 1, v[24:25]
	v_lshlrev_b32_e32 v2, 1, v20
	v_lshl_add_u64 v[24:25], v[24:25], 0, v[2:3]
	s_mov_b64 s[10:11], 0x14f00800
	v_pk_mul_f32 v[12:13], v[0:1], v[12:13] op_sel_hi:[0,1]
	v_pk_mul_f32 v[14:15], v[0:1], v[14:15] op_sel_hi:[0,1]
	v_pk_mul_f32 v[4:5], v[0:1], v[4:5] op_sel_hi:[0,1]
	v_pk_mul_f32 v[6:7], v[0:1], v[6:7] op_sel_hi:[0,1]
	v_pk_mul_f32 v[8:9], v[0:1], v[8:9] op_sel_hi:[0,1]
	v_pk_mul_f32 v[10:11], v[0:1], v[10:11] op_sel_hi:[0,1]
	v_pk_mul_f32 v[16:17], v[0:1], v[16:17] op_sel_hi:[0,1]
	v_pk_mul_f32 v[18:19], v[0:1], v[18:19] op_sel_hi:[0,1]
	v_cvt_pk_bf16_f32 v88, v12, v13
	v_cvt_pk_bf16_f32 v89, v14, v15
	v_cvt_pk_bf16_f32 v90, v4, v5
	v_cvt_pk_bf16_f32 v91, v6, v7
	v_cvt_pk_bf16_f32 v92, v8, v9
	v_cvt_pk_bf16_f32 v93, v10, v11
	v_cvt_pk_bf16_f32 v94, v16, v17
	v_cvt_pk_bf16_f32 v95, v18, v19
	v_mbcnt_lo_u32_b32 v96, -1, 0
	v_mbcnt_hi_u32_b32 v96, -1, v96
	v_permlane16_swap_b32 v88, v90
	v_permlane16_swap_b32 v89, v91
	v_permlane16_swap_b32 v92, v94
	v_permlane16_swap_b32 v93, v95
	v_and_b32_e32 v96, 16, v96
	v_lshrrev_b32_e32 v97, 1, v96
	v_add_u32_e32 v96, v96, v97
	v_add_co_u32_e32 v14, vcc, s61, v24
	s_nop 1
	v_addc_co_u32_e32 v15, vcc, 0, v25, vcc
	v_add_co_u32_e32 v14, vcc, v96, v14
	s_nop 1
	v_addc_co_u32_e32 v15, vcc, 0, v15, vcc
	global_store_dwordx4 v[14:15], v[88:91], off offset:2048
	global_store_dwordx4 v[14:15], v[92:95], off offset:2112
	s_branch .LBB0_1127
